# non-temporal hint on the streaming x-row loads of phases 6 and 9 (x is read once per phase and never reused from cache)
# speedup vs baseline: 1.0030x; 1.0030x over previous
; DI float bflo(unsigned u) { return __uint_as_float(u << 16); }
; DI float bfhi(unsigned u) { return __uint_as_float(u & 0xffff0000u); }
; DI void phase6(const Params& p) {
;     const int lane = VTID & 63, w = VTID >> 6;
;     const float* x = p.in[0]; const float* gpost = p.in[15]; const float* gffn = p.in[16];
;     const bf16_t* MIX = (const bf16_t*)(p.ws + OFF_MIX);
;     bf16_t* H = (bf16_t*)(p.ws + OFF_H);
;     float* RSTD = (float*)(p.ws + OFF_GATES);
;     for (int row = VBLK * 4 + w; row < T; row += VGRID * 4) {
;         f32x4 mv[4], xv[4]; float ss = 0.f;
; #pragma unroll
;         for (int i = 0; i < 4; ++i) {
;             const u32x2 u = *(const u32x2*)(MIX + (size_t)row * 1024 + i * 256 + lane * 4);
;             mv[i][0] = bflo(u.x); mv[i][1] = bfhi(u.x); mv[i][2] = bflo(u.y); mv[i][3] = bfhi(u.y);
;             xv[i] = *(const f32x4*)(x + (size_t)row * 1024 + i * 256 + lane * 4);
.LBB0_702:
	s_cmp_gt_i32 s90, 6
	s_cselect_b64 s[0:1], -1, 0
	s_cmp_lt_i32 s91, 7
	s_cselect_b64 s[2:3], -1, 0
	s_or_b64 s[0:1], s[0:1], s[2:3]
	v_bfe_u32 v1, v0, 6, 4
	s_and_b64 vcc, exec, s[0:1]
	v_and_b32_e32 v150, 4, v1
	s_cbranch_vccnz .LBB0_758
	v_and_b32_e32 v56, 0x3ff, v0
	v_readlane_b32 s0, v238, 0
	v_bfe_u32 v1, v56, 6, 2
	s_lshl_b32 s0, s0, 3
	v_or3_b32 v18, v150, s0, v1
	s_mov_b32 s0, 0x8000
	v_cmp_gt_i32_e32 vcc, s0, v18
	s_and_saveexec_b64 s[2:3], vcc
	s_cbranch_execz .LBB0_708
	v_mbcnt_lo_u32_b32 v2, -1, 0
	v_mbcnt_hi_u32_b32 v2, -1, v2
	v_and_b32_e32 v4, 64, v2
	v_xor_b32_e32 v3, 32, v2
	v_add_u32_e32 v4, 64, v4
	v_cmp_lt_i32_e32 vcc, v3, v4
	v_readlane_b32 s4, v238, 31
	v_readlane_b32 s5, v238, 32
	v_cndmask_b32_e32 v3, v2, v3, vcc
	v_lshlrev_b32_e32 v57, 2, v3
	v_xor_b32_e32 v3, 16, v2
	v_cmp_lt_i32_e32 vcc, v3, v4
	v_readlane_b32 s6, v238, 33
	v_readlane_b32 s7, v238, 34
	v_cndmask_b32_e32 v3, v2, v3, vcc
	v_lshlrev_b32_e32 v58, 2, v3
	v_xor_b32_e32 v3, 8, v2
	v_cmp_lt_i32_e32 vcc, v3, v4
	v_readlane_b32 s8, v238, 35
	v_readlane_b32 s9, v238, 36
	v_cndmask_b32_e32 v3, v2, v3, vcc
	v_lshlrev_b32_e32 v59, 2, v3
	v_xor_b32_e32 v3, 4, v2
	v_cmp_lt_i32_e32 vcc, v3, v4
	v_readlane_b32 s10, v238, 37
	v_readlane_b32 s11, v238, 38
	v_cndmask_b32_e32 v3, v2, v3, vcc
	v_lshlrev_b32_e32 v60, 2, v3
	v_xor_b32_e32 v3, 2, v2
	v_cmp_lt_i32_e32 vcc, v3, v4
	v_and_b32_e32 v1, 63, v56
	v_readlane_b32 s4, v238, 1
	v_cndmask_b32_e32 v3, v2, v3, vcc
	v_lshlrev_b32_e32 v61, 2, v3
	v_xor_b32_e32 v3, 1, v2
	v_cmp_lt_i32_e32 vcc, v3, v4
	v_readlane_b32 s12, v238, 39
	v_readlane_b32 s13, v238, 40
	v_cndmask_b32_e32 v2, v2, v3, vcc
	v_lshlrev_b32_e32 v62, 2, v2
	v_lshlrev_b32_e32 v2, 4, v1
	v_mov_b32_e32 v3, 0
	v_readlane_b32 s14, v238, 41
	v_readlane_b32 s15, v238, 42
	v_readlane_b32 s16, v238, 43
	v_readlane_b32 s17, v238, 44
	v_readlane_b32 s18, v238, 45
	v_readlane_b32 s19, v238, 46
	v_readlane_b32 s5, v238, 2
	v_ashrrev_i32_e32 v19, 31, v18
	v_mov_b64_e32 v[4:5], 0x18ba5800
	v_lshl_add_u64 v[20:21], s[18:19], 0, v[2:3]
	v_readlane_b32 s6, v238, 3
	v_lshl_add_u64 v[22:23], s[4:5], 0, v[2:3]
	v_readlane_b32 s4, v238, 10
	v_lshl_add_u64 v[24:25], v[18:19], 2, v[4:5]
	v_lshlrev_b64 v[4:5], 12, v[18:19]
	v_readlane_b32 s12, v238, 15
	v_readlane_b32 s7, v238, 4
	v_readlane_b32 s5, v238, 11
	s_lshl_b32 s6, s4, 3
	v_or_b32_e32 v4, v4, v2
	v_readlane_b32 s13, v238, 16
	v_readlane_b32 s8, v238, 5
	v_readlane_b32 s9, v238, 6
	v_readlane_b32 s10, v238, 7
	v_readlane_b32 s11, v238, 8
	s_ashr_i32 s7, s6, 31
	v_lshlrev_b64 v[26:27], 11, v[18:19]
	v_readlane_b32 s14, v238, 17
	v_readlane_b32 s15, v238, 18
	v_readlane_b32 s16, v238, 19
	v_readlane_b32 s17, v238, 20
	v_lshl_add_u64 v[2:3], s[12:13], 0, v[4:5]
	s_mov_b64 s[4:5], 0xc00
	v_cmp_eq_u32_e64 s[0:1], 0, v1
	s_lshl_b64 s[8:9], s[6:7], 2
	v_lshl_or_b32 v26, v1, 3, v26
	s_lshl_b64 s[10:11], s[6:7], 11
	v_lshl_add_u64 v[28:29], v[2:3], 0, s[4:5]
	s_lshl_b64 s[12:13], s[6:7], 12
	s_mov_b64 s[14:15], 0
	v_mov_b32_e32 v63, 0x358637bd
	s_mov_b32 s7, 0x800000
	s_mov_b32 s16, 0x1ba5000
	s_movk_i32 s17, 0x7fff
	v_readlane_b32 s18, v238, 21
	v_readlane_b32 s19, v238, 22
	v_readlane_b32 s20, v238, 23
	v_readlane_b32 s21, v238, 24
	v_readlane_b32 s22, v238, 25
	v_readlane_b32 s23, v238, 26
	v_readlane_b32 s24, v238, 27
	v_readlane_b32 s25, v238, 28
	v_readlane_b32 s26, v238, 29
	v_readlane_b32 s27, v238, 30
	global_load_dwordx4 v[200:203], v[20:21], off
	global_load_dwordx4 v[204:207], v[20:21], off offset:1024
	global_load_dwordx4 v[208:211], v[20:21], off offset:2048
	global_load_dwordx4 v[212:215], v[20:21], off offset:3072
	global_load_dwordx4 v[216:219], v[22:23], off
	global_load_dwordx4 v[220:223], v[22:23], off offset:1024
	global_load_dwordx4 v[224:227], v[22:23], off offset:2048
	global_load_dwordx4 v[228:231], v[22:23], off offset:3072
	v_lshl_add_u64 v[96:97], s[88:89], 0, v[26:27]
	v_add_co_u32_e32 v96, vcc, 0x9ba5000, v96
	s_nop 1
	v_addc_co_u32_e32 v97, vcc, 0, v97, vcc
	v_mov_b32_e32 v98, v28
	v_mov_b32_e32 v99, v29
	global_load_dwordx2 v[70:71], v[96:97], off offset:2048
	global_load_dwordx2 v[72:73], v[96:97], off offset:2560
	global_load_dwordx2 v[74:75], v[96:97], off offset:3072
	global_load_dwordx2 v[76:77], v[96:97], off offset:3584
	global_load_dwordx4 v[80:83], v[98:99], off offset:-3072 nt
	global_load_dwordx4 v[84:87], v[98:99], off offset:-2048 nt
	global_load_dwordx4 v[88:91], v[98:99], off offset:-1024 nt
	global_load_dwordx4 v[92:95], v[98:99], off nt
	s_waitcnt vmcnt(0)
	s_branch .Lp6_in

; DI float bflo(unsigned u) { return __uint_as_float(u << 16); }
; DI float bfhi(unsigned u) { return __uint_as_float(u & 0xffff0000u); }
; DI void phase6(const Params& p) {
;     ...
;     for (int row = VBLK * 4 + w; row < T; row += VGRID * 4) {
;         f32x4 mv[4], xv[4]; float ss = 0.f;
; #pragma unroll
;         for (int i = 0; i < 4; ++i) {
;             const u32x2 u = *(const u32x2*)(MIX + (size_t)row * 1024 + i * 256 + lane * 4);
;             mv[i][0] = bflo(u.x); mv[i][1] = bfhi(u.x); mv[i][2] = bflo(u.y); mv[i][3] = bfhi(u.y);
;             xv[i] = *(const f32x4*)(x + (size_t)row * 1024 + i * 256 + lane * 4);
.Lp6_in:
	v_lshl_add_u64 v[30:31], s[88:89], 0, v[26:27]
	v_mov_b32_e32 v34, v70
	v_mov_b32_e32 v35, v71
	v_mov_b32_e32 v38, v72
	v_mov_b32_e32 v39, v73
	v_mov_b32_e32 v42, v74
	v_mov_b32_e32 v43, v75
	v_mov_b32_e32 v54, v76
	v_mov_b32_e32 v55, v77
	v_mov_b32_e32 v14, v80
	v_mov_b32_e32 v15, v81
	v_mov_b32_e32 v16, v82
	v_mov_b32_e32 v17, v83
	v_mov_b32_e32 v10, v84
	v_mov_b32_e32 v11, v85
	v_mov_b32_e32 v12, v86
	v_mov_b32_e32 v13, v87
	v_mov_b32_e32 v2, v88
	v_mov_b32_e32 v3, v89
	v_mov_b32_e32 v4, v90
	v_mov_b32_e32 v5, v91
	v_mov_b32_e32 v6, v92
	v_mov_b32_e32 v7, v93
	v_mov_b32_e32 v8, v94
	v_mov_b32_e32 v9, v95
	v_add_u32_e32 v98, s6, v18
	v_cmp_ge_i32_e32 vcc, s17, v98
	s_and_saveexec_b64 s[98:99], vcc
	s_cbranch_execz .Lp6_nopf
	v_lshl_add_u64 v[96:97], v[30:31], 0, s[10:11]
	v_add_co_u32_e32 v96, vcc, 0x9ba5000, v96
	s_nop 1
	v_addc_co_u32_e32 v97, vcc, 0, v97, vcc
	v_lshl_add_u64 v[98:99], v[28:29], 0, s[12:13]
	global_load_dwordx2 v[70:71], v[96:97], off offset:2048
	global_load_dwordx2 v[72:73], v[96:97], off offset:2560
	global_load_dwordx2 v[74:75], v[96:97], off offset:3072
	global_load_dwordx2 v[76:77], v[96:97], off offset:3584
	global_load_dwordx4 v[80:83], v[98:99], off offset:-3072 nt
	global_load_dwordx4 v[84:87], v[98:99], off offset:-2048 nt
	global_load_dwordx4 v[88:91], v[98:99], off offset:-1024 nt
	global_load_dwordx4 v[92:95], v[98:99], off nt

; DI float bflo(unsigned u) { return __uint_as_float(u << 16); }
; DI float bfhi(unsigned u) { return __uint_as_float(u & 0xffff0000u); }
; DI void phase9(const Params& p) {
;     const int lane = VTID & 63, w = VTID >> 6;
;     const float* x = p.in[0]; const float* g1 = p.in[15]; const float* g2 = p.in[20];
;     const bf16_t* MIX = (const bf16_t*)(p.ws + OFF_MIX);
;     const bf16_t* F = (const bf16_t*)(p.ws + OFF_O);
;     const float* RSTD = (const float*)(p.ws + OFF_GATES);
;     for (int row = VBLK * 4 + w; row < T; row += VGRID * 4) {
;         f32x4 fv[4], mv[4]; float ss = 0.f;
; #pragma unroll
;         for (int i = 0; i < 4; ++i) {
;             const u32x2 u = *(const u32x2*)(F + (size_t)row * 1024 + i * 256 + lane * 4);
;             fv[i][0] = bflo(u.x); fv[i][1] = bfhi(u.x); fv[i][2] = bflo(u.y); fv[i][3] = bfhi(u.y);
;             const u32x2 um = *(const u32x2*)(MIX + (size_t)row * 1024 + i * 256 + lane * 4);
;             mv[i][0] = bflo(um.x); mv[i][1] = bfhi(um.x); mv[i][2] = bflo(um.y); mv[i][3] = bfhi(um.y);
;             ss += fv[i][0] * fv[i][0] + fv[i][1] * fv[i][1] + fv[i][2] * fv[i][2] + fv[i][3] * fv[i][3];
;         }
;         ss = wave_sum(ss);
;         const float rstd = rsqrtf(ss * (1.f / 1024.f) + NORM_EPS);
;         const float rstd1 = RSTD[row];
; #pragma unroll
;         for (int i = 0; i < 4; ++i) {
;             const f32x4 ga = *(const f32x4*)(g1 + i * 256 + lane * 4);
;             const f32x4 gb = *(const f32x4*)(g2 + i * 256 + lane * 4);
;             f32x4 xv = *(const f32x4*)(x + (size_t)row * 1024 + i * 256 + lane * 4);
.LBB0_904:
	s_cmp_gt_i32 s90, 9
	s_cselect_b64 s[0:1], -1, 0
	s_cmp_lt_i32 s91, 10
	s_cselect_b64 s[2:3], -1, 0
	s_or_b64 s[0:1], s[0:1], s[2:3]
	s_and_b64 vcc, exec, s[0:1]
	s_cbranch_vccnz .LBB0_958
	v_and_b32_e32 v14, 0x3ff, v0
	v_readlane_b32 s0, v238, 0
	v_bfe_u32 v0, v14, 6, 2
	s_lshl_b32 s0, s0, 3
	v_or3_b32 v0, v150, s0, v0
	s_mov_b32 s0, 0x8000
	v_cmp_gt_i32_e32 vcc, s0, v0
	s_and_saveexec_b64 s[0:1], vcc
	v_readlane_b32 s16, v238, 15
	v_readlane_b32 s17, v238, 16
	v_readlane_b32 s18, v238, 17
	v_readlane_b32 s19, v238, 18
	v_readlane_b32 s20, v238, 19
	v_readlane_b32 s21, v238, 20
	v_readlane_b32 s22, v238, 21
	v_readlane_b32 s23, v238, 22
	v_readlane_b32 s24, v238, 23
	v_readlane_b32 s25, v238, 24
	v_readlane_b32 s26, v238, 25
	v_readlane_b32 s27, v238, 26
	v_readlane_b32 s28, v238, 27
	v_readlane_b32 s29, v238, 28
	v_readlane_b32 s30, v238, 29
	v_readlane_b32 s31, v238, 30
	s_cbranch_execz .LBB0_908
	v_mbcnt_lo_u32_b32 v1, -1, 0
	v_mbcnt_hi_u32_b32 v1, -1, v1
	v_and_b32_e32 v3, 64, v1
	v_xor_b32_e32 v2, 32, v1
	v_add_u32_e32 v3, 64, v3
	v_cmp_lt_i32_e32 vcc, v2, v3
	v_readlane_b32 s2, v238, 10
	v_readlane_b32 s36, v238, 31
	v_cndmask_b32_e32 v2, v1, v2, vcc
	v_lshlrev_b32_e32 v15, 2, v2
	v_xor_b32_e32 v2, 16, v1
	v_cmp_lt_i32_e32 vcc, v2, v3
	v_readlane_b32 s3, v238, 11
	s_lshl_b32 s2, s2, 3
	v_cndmask_b32_e32 v2, v1, v2, vcc
	v_lshlrev_b32_e32 v16, 2, v2
	v_xor_b32_e32 v2, 8, v1
	v_cmp_lt_i32_e32 vcc, v2, v3
	v_mov_b32_e32 v5, 0
	v_readlane_b32 s50, v238, 45
	v_cndmask_b32_e32 v2, v1, v2, vcc
	v_lshlrev_b32_e32 v17, 2, v2
	v_xor_b32_e32 v2, 4, v1
	v_cmp_lt_i32_e32 vcc, v2, v3
	v_readlane_b32 s51, v238, 46
	v_mov_b64_e32 v[6:7], 0x18ba5800
	v_cndmask_b32_e32 v2, v1, v2, vcc
	v_lshlrev_b32_e32 v18, 2, v2
	v_xor_b32_e32 v2, 2, v1
	v_cmp_lt_i32_e32 vcc, v2, v3
	s_ashr_i32 s3, s2, 31
	v_and_b32_e32 v12, 63, v14
	v_cndmask_b32_e32 v2, v1, v2, vcc
	v_lshlrev_b32_e32 v19, 2, v2
	v_xor_b32_e32 v2, 1, v1
	v_cmp_lt_i32_e32 vcc, v2, v3
	s_lshl_b64 s[4:5], s[2:3], 2
	s_lshl_b64 s[6:7], s[2:3], 12
	v_cndmask_b32_e32 v1, v1, v2, vcc
	v_lshlrev_b32_e32 v20, 2, v1
	v_lshlrev_b32_e32 v1, 4, v14
	v_and_b32_e32 v4, 0x3f0, v1
	v_ashrrev_i32_e32 v1, 31, v0
	v_lshlrev_b64 v[8:9], 12, v[0:1]
	v_lshlrev_b64 v[10:11], 11, v[0:1]
	v_lshl_add_u64 v[2:3], s[50:51], 0, v[4:5]
	v_lshl_add_u64 v[4:5], s[84:85], 0, v[4:5]
	v_lshl_add_u64 v[6:7], v[0:1], 2, v[6:7]
	v_lshl_or_b32 v8, v12, 4, v8
	v_lshl_or_b32 v10, v12, 3, v10
	s_lshl_b64 s[8:9], s[2:3], 11
	s_mov_b64 s[10:11], 0
	v_mov_b32_e32 v1, 0x358637bd
	s_mov_b32 s3, 0x800000
	s_movk_i32 s12, 0x7fff
	v_readlane_b32 s37, v238, 32
	v_readlane_b32 s38, v238, 33
	v_readlane_b32 s39, v238, 34
	v_readlane_b32 s40, v238, 35
	v_readlane_b32 s41, v238, 36
	v_readlane_b32 s42, v238, 37
	v_readlane_b32 s43, v238, 38
	v_readlane_b32 s44, v238, 39
	v_readlane_b32 s45, v238, 40
	v_readlane_b32 s46, v238, 41
	v_readlane_b32 s47, v238, 42
	v_readlane_b32 s48, v238, 43
	v_readlane_b32 s49, v238, 44
	global_load_dwordx4 v[200:203], v[2:3], off
	global_load_dwordx4 v[204:207], v[2:3], off offset:1024
	global_load_dwordx4 v[208:211], v[2:3], off offset:2048
	global_load_dwordx4 v[212:215], v[2:3], off offset:3072
	global_load_dwordx4 v[216:219], v[4:5], off
	global_load_dwordx4 v[220:223], v[4:5], off offset:1024
	global_load_dwordx4 v[224:227], v[4:5], off offset:2048
	global_load_dwordx4 v[228:231], v[4:5], off offset:3072
	s_waitcnt vmcnt(0)
	v_lshl_add_u64 v[140:141], s[88:89], 0, v[10:11]
	v_add_co_u32_e32 v138, vcc, 0x5ba5000, v140
	v_lshl_add_u64 v[136:137], s[88:89], 0, v[6:7]
	s_nop 0
	v_addc_co_u32_e32 v139, vcc, 0, v141, vcc
	v_lshl_add_u64 v[142:143], s[16:17], 0, v[8:9]
	v_add_co_u32_e32 v140, vcc, 0x9ba5000, v140
	s_nop 1
	v_addc_co_u32_e32 v141, vcc, 0, v141, vcc
	global_load_dword v100, v[136:137], off
	global_load_dwordx2 v[102:103], v[138:139], off offset:2048
	global_load_dwordx2 v[104:105], v[138:139], off offset:2560
	global_load_dwordx2 v[106:107], v[138:139], off offset:3072
	global_load_dwordx2 v[108:109], v[138:139], off offset:3584
	global_load_dwordx2 v[110:111], v[140:141], off offset:2048
	global_load_dwordx2 v[112:113], v[140:141], off offset:2560
	global_load_dwordx2 v[114:115], v[140:141], off offset:3072
	global_load_dwordx2 v[116:117], v[140:141], off offset:3584
	global_load_dwordx4 v[120:123], v[142:143], off nt
	global_load_dwordx4 v[124:127], v[142:143], off offset:1024 nt
	global_load_dwordx4 v[128:131], v[142:143], off offset:2048 nt
	global_load_dwordx4 v[132:135], v[142:143], off offset:3072 nt
	s_waitcnt vmcnt(0)
	s_branch .Lp9_in

; DI float bflo(unsigned u) { return __uint_as_float(u << 16); }
; DI float bfhi(unsigned u) { return __uint_as_float(u & 0xffff0000u); }
; DI void phase9(const Params& p) {
;     ...
;     for (int row = VBLK * 4 + w; row < T; row += VGRID * 4) {
;         f32x4 fv[4], mv[4]; float ss = 0.f;
; #pragma unroll
;         for (int i = 0; i < 4; ++i) {
;             const u32x2 u = *(const u32x2*)(F + (size_t)row * 1024 + i * 256 + lane * 4);
;             fv[i][0] = bflo(u.x); fv[i][1] = bfhi(u.x); fv[i][2] = bflo(u.y); fv[i][3] = bfhi(u.y);
;             const u32x2 um = *(const u32x2*)(MIX + (size_t)row * 1024 + i * 256 + lane * 4);
;             mv[i][0] = bflo(um.x); mv[i][1] = bfhi(um.x); mv[i][2] = bflo(um.y); mv[i][3] = bfhi(um.y);
;             ss += fv[i][0] * fv[i][0] + fv[i][1] * fv[i][1] + fv[i][2] * fv[i][2] + fv[i][3] * fv[i][3];
;         }
;         ss = wave_sum(ss);
;         const float rstd = rsqrtf(ss * (1.f / 1024.f) + NORM_EPS);
;         const float rstd1 = RSTD[row];
; #pragma unroll
;         for (int i = 0; i < 4; ++i) {
;             const f32x4 ga = *(const f32x4*)(g1 + i * 256 + lane * 4);
;             const f32x4 gb = *(const f32x4*)(g2 + i * 256 + lane * 4);
;             f32x4 xv = *(const f32x4*)(x + (size_t)row * 1024 + i * 256 + lane * 4);
.Lp9_in:
	v_lshl_add_u64 v[12:13], s[86:87], 0, v[8:9]
	v_mov_b32_e32 v42, v100
	v_mov_b32_e32 v36, v102
	v_mov_b32_e32 v37, v103
	v_mov_b32_e32 v44, v104
	v_mov_b32_e32 v45, v105
	v_mov_b32_e32 v46, v106
	v_mov_b32_e32 v47, v107
	v_mov_b32_e32 v48, v108
	v_mov_b32_e32 v49, v109
	v_mov_b32_e32 v40, v110
	v_mov_b32_e32 v41, v111
	v_mov_b32_e32 v50, v112
	v_mov_b32_e32 v51, v113
	v_mov_b32_e32 v52, v114
	v_mov_b32_e32 v53, v115
	v_mov_b32_e32 v54, v116
	v_mov_b32_e32 v55, v117
	v_mov_b32_e32 v30, v120
	v_mov_b32_e32 v31, v121
	v_mov_b32_e32 v32, v122
	v_mov_b32_e32 v33, v123
	v_mov_b32_e32 v80, v124
	v_mov_b32_e32 v81, v125
	v_mov_b32_e32 v82, v126
	v_mov_b32_e32 v83, v127
	v_mov_b32_e32 v84, v128
	v_mov_b32_e32 v85, v129
	v_mov_b32_e32 v86, v130
	v_mov_b32_e32 v87, v131
	v_mov_b32_e32 v88, v132
	v_mov_b32_e32 v89, v133
	v_mov_b32_e32 v90, v134
	v_mov_b32_e32 v91, v135
	v_add_u32_e32 v0, s2, v0
	v_lshl_add_u64 v[6:7], v[6:7], 0, s[4:5]
	v_lshl_add_u64 v[8:9], v[8:9], 0, s[6:7]
	v_lshl_add_u64 v[10:11], v[10:11], 0, s[8:9]
	v_cmp_ge_i32_e32 vcc, s12, v0
	s_and_saveexec_b64 s[98:99], vcc
	s_cbranch_execz .Lp9_nopf
	v_lshl_add_u64 v[140:141], s[88:89], 0, v[10:11]
	v_add_co_u32_e32 v138, vcc, 0x5ba5000, v140
	v_lshl_add_u64 v[136:137], s[88:89], 0, v[6:7]
	s_nop 0
	v_addc_co_u32_e32 v139, vcc, 0, v141, vcc
	v_lshl_add_u64 v[142:143], s[16:17], 0, v[8:9]
	v_add_co_u32_e32 v140, vcc, 0x9ba5000, v140
	s_nop 1
	v_addc_co_u32_e32 v141, vcc, 0, v141, vcc
	global_load_dword v100, v[136:137], off
	global_load_dwordx2 v[102:103], v[138:139], off offset:2048
	global_load_dwordx2 v[104:105], v[138:139], off offset:2560
	global_load_dwordx2 v[106:107], v[138:139], off offset:3072
	global_load_dwordx2 v[108:109], v[138:139], off offset:3584
	global_load_dwordx2 v[110:111], v[140:141], off offset:2048
	global_load_dwordx2 v[112:113], v[140:141], off offset:2560
	global_load_dwordx2 v[114:115], v[140:141], off offset:3072
	global_load_dwordx2 v[116:117], v[140:141], off offset:3584
	global_load_dwordx4 v[120:123], v[142:143], off nt
	global_load_dwordx4 v[124:127], v[142:143], off offset:1024 nt
	global_load_dwordx4 v[128:131], v[142:143], off offset:2048 nt
	global_load_dwordx4 v[132:135], v[142:143], off offset:3072 nt
